# attention loops: LDS-write wait + barrier moved below the next tile's global loads (load issue overlaps LDS write latency)
# baseline (speedup 1.0000x reference)
; #define ATT_LOADK(t, r0, r1) do { r0 = *(const u32x4*)(kg0 + (size_t)(t) * 64 * DK); if (k1on) r1 = *(const u32x4*)(kg1 + (size_t)(t) * 64 * DK); } while (0)
; #define ATT_LOADV(t, r0, r1) do { if (von) { r0 = *(const u32x4*)(vg0 + (size_t)(t) * 64 * DV); r1 = *(const u32x4*)(vg0 + (size_t)(t) * 64 * DV + DV); } } while (0)
; #define ATT_STOREK(bi, r0, r1) do { LAS unsigned char* kb_ = lds + (bi) * ATT_BUF; *(LAS u32x4*)(kb_ + kl0) = r0; if (k1on) *(LAS u32x4*)(kb_ + kl1) = r1; } while (0)
; template <int DK, int DV, int VAR>
; __device__ __forceinline__ void attn_pass(LAS unsigned char* lds, const bf16_t* Qg, const bf16_t* Kg, const bf16_t* Vg, int ntiles, float cs, f32x16 (&O)[DV / 32], float& lsum, int wv) {
;     ...
;         if (VAR != 1 || t < 2) { ATT_STOREK(t & 1, ka0, ka1); ATT_STOREV(t & 1, va0, va1); }
;         __syncthreads();
;         if (VAR != 1) { if (t + 1 < ntiles) { ATT_LOADK(t + 1, ka0, ka1); ATT_LOADV(t + 1, va0, va1); } }
.LBB0_930:
	s_or_b64 exec, exec, s[8:9]
	v_lshl_add_u64 v[32:33], s[0:1], 0, v[174:175]
	global_load_dwordx4 v[132:135], v[32:33], off
	s_and_saveexec_b64 s[8:9], s[2:3]
	s_cbranch_execz .LBB0_932
	v_lshl_add_u64 v[32:33], s[0:1], 0, v[172:173]
	global_load_dwordx4 v[124:127], v[32:33], off

.LBB0_934:
	s_or_b64 exec, exec, s[8:9]
	v_add3_u32 v64, s18, v190, v168
	s_waitcnt lgkmcnt(0)
	s_barrier
	ds_read_b128 v[32:35], v64
	ds_read_b128 v[36:39], v64 offset:0x1a00
	ds_read_b128 v[40:43], v64 offset:32
	ds_read_b128 v[44:47], v64 offset:0x1a20
	ds_read_b128 v[136:139], v64 offset:64
	ds_read_b128 v[140:143], v64 offset:0x1a40
	ds_read_b128 v[144:147], v64 offset:96
	ds_read_b128 v[148:151], v64 offset:0x1a60
	ds_read_b128 v[152:155], v64 offset:128
	ds_read_b128 v[156:159], v64 offset:0x1a80
	ds_read_b128 v[206:209], v64 offset:160
	ds_read_b128 v[160:163], v64 offset:0x1aa0
	s_nop 0
	s_waitcnt lgkmcnt(11)
	v_mfma_f32_32x32x16_bf16 v[80:95], v[32:35], v[116:119], v[48:63]
	v_add_u32_e32 v32, s18, v191
	v_add3_u32 v32, v32, v189, s87
	s_waitcnt lgkmcnt(10)
	v_mfma_f32_32x32x16_bf16 v[64:79], v[36:39], v[116:119], v[48:63]
	s_waitcnt lgkmcnt(9)
	v_mfma_f32_32x32x16_bf16 v[80:95], v[40:43], v[112:115], v[80:95]
	s_waitcnt lgkmcnt(8)
	v_mfma_f32_32x32x16_bf16 v[64:79], v[44:47], v[112:115], v[64:79]
	s_waitcnt lgkmcnt(7)
	v_mfma_f32_32x32x16_bf16 v[80:95], v[136:139], v[108:111], v[80:95]
	s_waitcnt lgkmcnt(6)
	v_mfma_f32_32x32x16_bf16 v[64:79], v[140:143], v[108:111], v[64:79]
	s_waitcnt lgkmcnt(5)
	v_mfma_f32_32x32x16_bf16 v[80:95], v[144:147], v[104:107], v[80:95]
	s_waitcnt lgkmcnt(4)
	v_mfma_f32_32x32x16_bf16 v[64:79], v[148:151], v[104:107], v[64:79]
	s_waitcnt lgkmcnt(3)
	v_mfma_f32_32x32x16_bf16 v[80:95], v[152:155], v[100:103], v[80:95]
	s_waitcnt lgkmcnt(2)
	v_mfma_f32_32x32x16_bf16 v[64:79], v[156:159], v[100:103], v[64:79]
	s_waitcnt lgkmcnt(0)
	v_mfma_f32_32x32x16_bf16 v[64:79], v[160:163], v[96:99], v[64:79]
	ds_read_b64 v[164:165], v32
	ds_read_b64 v[166:167], v32 offset:16
	ds_read_b64 v[160:161], v32 offset:32
	ds_read_b64 v[162:163], v32 offset:48
	ds_read_b64 v[156:157], v32 offset:64
	ds_read_b64 v[158:159], v32 offset:80
	ds_read_b64 v[152:153], v32 offset:96
	ds_read_b64 v[154:155], v32 offset:112
	ds_read_b64 v[148:149], v32 offset:0x1100
	ds_read_b64 v[150:151], v32 offset:0x1110
	ds_read_b64 v[144:145], v32 offset:0x1120
	ds_read_b64 v[146:147], v32 offset:0x1130
	ds_read_b64 v[140:141], v32 offset:0x1140
	ds_read_b64 v[142:143], v32 offset:0x1150
	ds_read_b64 v[136:137], v32 offset:0x1160
	ds_read_b64 v[138:139], v32 offset:0x1170
	v_mfma_f32_32x32x16_bf16 v[80:95], v[206:209], v[96:99], v[80:95]
	v_max3_f32 v33, v64, v65, v66
	v_max3_f32 v33, v33, v67, v68
	v_max3_f32 v33, v33, v69, v70
	v_max3_f32 v33, v33, v71, v72
	v_max3_f32 v33, v33, v73, v74
	v_max3_f32 v33, v33, v75, v76
	v_max3_f32 v33, v33, v77, v78
	v_max_f32_e32 v33, v33, v79
	s_nop 3
	v_max3_f32 v32, v80, v81, v82
	v_max3_f32 v34, v83, v84, v85
	v_max3_f32 v32, v32, v86, v87
	v_max3_f32 v34, v34, v88, v89
	v_max3_f32 v32, v32, v90, v91
	v_max3_f32 v34, v34, v92, v93
	v_max3_f32 v32, v32, v94, v95
	v_max3_f32 v32, v32, v34, v33
	v_mov_b32_e32 v33, v32
	s_nop 1
	v_permlane32_swap_b32_e32 v32, v33
	v_max_f32_e32 v32, v32, v33
	v_cmp_lt_f32_e32 vcc, s80, v32
	s_cbranch_vccz .LBB0_936
	v_max_f32_e32 v48, 0, v32
	v_exp_f32_e64 v32, -v48
	s_nop 0
	v_mov_b32_e32 v49, v32
	v_pk_mul_f32 v[30:31], v[30:31], v[32:33] op_sel_hi:[1,0]
	v_pk_mul_f32 v[28:29], v[28:29], v[32:33] op_sel_hi:[1,0]
	v_pk_mul_f32 v[26:27], v[26:27], v[32:33] op_sel_hi:[1,0]
	v_pk_mul_f32 v[24:25], v[24:25], v[32:33] op_sel_hi:[1,0]
	v_pk_mul_f32 v[22:23], v[22:23], v[32:33] op_sel_hi:[1,0]
	v_pk_mul_f32 v[20:21], v[20:21], v[32:33] op_sel_hi:[1,0]
	v_pk_mul_f32 v[18:19], v[18:19], v[32:33] op_sel_hi:[1,0]
	v_pk_mul_f32 v[14:15], v[14:15], v[32:33] op_sel_hi:[1,0]
	v_pk_mul_f32 v[12:13], v[12:13], v[32:33] op_sel_hi:[1,0]
	v_pk_mul_f32 v[10:11], v[10:11], v[32:33] op_sel_hi:[1,0]
	v_pk_mul_f32 v[8:9], v[8:9], v[32:33] op_sel_hi:[1,0]
	v_pk_mul_f32 v[6:7], v[6:7], v[32:33] op_sel_hi:[1,0]
	v_pk_mul_f32 v[4:5], v[4:5], v[32:33] op_sel_hi:[1,0]
	v_pk_mul_f32 v[2:3], v[2:3], v[32:33] op_sel_hi:[1,0]
	v_pk_mul_f32 v[16:17], v[16:17], v[32:33] op_sel_hi:[1,0]
	v_pk_mul_f32 v[0:1], v[0:1], v[32:33] op_sel_hi:[1,0]
	v_pk_add_f32 v[178:179], v[176:177], v[48:49]
	v_pk_mul_f32 v[32:33], v[176:177], v[48:49]
	v_pk_add_f32 v[80:81], v[80:81], v[48:49] op_sel_hi:[1,0] neg_lo:[0,1] neg_hi:[0,1]
	v_mov_b32_e32 v179, v33
	v_pk_add_f32 v[32:33], v[178:179], 0 neg_lo:[1,1] neg_hi:[1,1]
	v_pk_add_f32 v[64:65], v[64:65], v[48:49] op_sel_hi:[1,0] neg_lo:[0,1] neg_hi:[0,1]
	v_pk_add_f32 v[82:83], v[82:83], v[48:49] op_sel_hi:[1,0] neg_lo:[0,1] neg_hi:[0,1]
	v_pk_add_f32 v[66:67], v[66:67], v[48:49] op_sel_hi:[1,0] neg_lo:[0,1] neg_hi:[0,1]
	v_pk_add_f32 v[84:85], v[84:85], v[48:49] op_sel_hi:[1,0] neg_lo:[0,1] neg_hi:[0,1]
	v_pk_add_f32 v[68:69], v[68:69], v[48:49] op_sel_hi:[1,0] neg_lo:[0,1] neg_hi:[0,1]
	v_pk_add_f32 v[86:87], v[86:87], v[48:49] op_sel_hi:[1,0] neg_lo:[0,1] neg_hi:[0,1]
	v_pk_add_f32 v[70:71], v[70:71], v[48:49] op_sel_hi:[1,0] neg_lo:[0,1] neg_hi:[0,1]
	v_pk_add_f32 v[88:89], v[88:89], v[48:49] op_sel_hi:[1,0] neg_lo:[0,1] neg_hi:[0,1]
	v_pk_add_f32 v[72:73], v[72:73], v[48:49] op_sel_hi:[1,0] neg_lo:[0,1] neg_hi:[0,1]
	v_pk_add_f32 v[90:91], v[90:91], v[48:49] op_sel_hi:[1,0] neg_lo:[0,1] neg_hi:[0,1]
	v_pk_add_f32 v[74:75], v[74:75], v[48:49] op_sel_hi:[1,0] neg_lo:[0,1] neg_hi:[0,1]
	v_pk_add_f32 v[92:93], v[92:93], v[48:49] op_sel_hi:[1,0] neg_lo:[0,1] neg_hi:[0,1]
	v_pk_add_f32 v[76:77], v[76:77], v[48:49] op_sel_hi:[1,0] neg_lo:[0,1] neg_hi:[0,1]
	v_mov_b32_e32 v33, v32
	v_mov_b32_e32 v34, v32
	v_mov_b32_e32 v35, v32
	v_mov_b32_e32 v36, v32
	v_mov_b32_e32 v37, v32
	v_mov_b32_e32 v38, v32
	v_mov_b32_e32 v39, v32
	v_mov_b32_e32 v40, v32
	v_mov_b32_e32 v41, v32
	v_mov_b32_e32 v42, v32
	v_mov_b32_e32 v43, v32
	v_mov_b32_e32 v44, v32
	v_mov_b32_e32 v45, v32
	v_mov_b32_e32 v46, v32
	v_mov_b32_e32 v47, v32
	v_pk_add_f32 v[94:95], v[94:95], v[48:49] op_sel_hi:[1,0] neg_lo:[0,1] neg_hi:[0,1]
	v_pk_add_f32 v[78:79], v[78:79], v[48:49] op_sel_hi:[1,0] neg_lo:[0,1] neg_hi:[0,1]
	v_mov_b32_e32 v48, v32
	v_mov_b32_e32 v49, v32
	v_mov_b32_e32 v50, v32
	v_mov_b32_e32 v51, v32
	v_mov_b32_e32 v52, v32
	v_mov_b32_e32 v53, v32
	v_mov_b32_e32 v54, v32
	v_mov_b32_e32 v55, v32
	v_mov_b32_e32 v56, v32
	v_mov_b32_e32 v57, v32
	v_mov_b32_e32 v58, v32
	v_mov_b32_e32 v59, v32
	v_mov_b32_e32 v60, v32
	v_mov_b32_e32 v61, v32
	v_mov_b32_e32 v62, v32
	v_mov_b32_e32 v63, v32
	v_mov_b32_e32 v176, v178
	s_branch .LBB0_937

.LBB0_955:
	s_and_b32 s0, s28, 0x8000
	s_add_i32 s29, s0, 0
	v_add3_u32 v64, s29, v205, v220
	s_waitcnt vmcnt(2)
	ds_write_b128 v64, v[148:151]
	s_and_saveexec_b64 s[0:1], s[2:3]
	v_add3_u32 v64, s29, v219, v221
	ds_write_b128 v64, v[144:147]
	s_or_b64 exec, exec, s[0:1]
	v_add3_u32 v64, s29, v240, v241
	s_waitcnt vmcnt(0)
	v_perm_b32 v65, v156, v152, s85
	v_perm_b32 v66, v156, v152, s86
	v_add_u32_e32 v64, 0x3400, v64
	ds_write2_b32 v64, v65, v66 offset1:34
	v_perm_b32 v65, v157, v153, s85
	v_perm_b32 v66, v157, v153, s86
	ds_write2_b32 v64, v65, v66 offset0:68 offset1:102
	v_perm_b32 v65, v158, v154, s85
	v_perm_b32 v66, v158, v154, s86
	ds_write2_b32 v64, v65, v66 offset0:136 offset1:170
	v_perm_b32 v65, v159, v155, s85
	v_perm_b32 v66, v159, v155, s86
	ds_write2_b32 v64, v65, v66 offset0:204 offset1:238
	v_lshl_add_u64 v[64:65], s[4:5], 0, v[210:211]
	global_load_dwordx4 v[148:151], v[64:65], off
	s_and_saveexec_b64 s[0:1], s[2:3]
	s_cbranch_execz .LBB0_959
	v_lshl_add_u64 v[64:65], s[4:5], 0, v[208:209]
	global_load_dwordx4 v[144:147], v[64:65], off
.LBB0_959:
	s_or_b64 exec, exec, s[0:1]
	v_lshl_add_u64 v[64:65], s[4:5], 0, v[206:207]
	v_add_co_u32_e32 v64, vcc, 0xa808000, v64
	v_add3_u32 v96, s29, v245, v204
	s_nop 0
	v_addc_co_u32_e32 v65, vcc, 0, v65, vcc
	global_load_dwordx4 v[152:155], v[64:65], off
	global_load_dwordx4 v[156:159], v[64:65], off offset:256
	s_waitcnt lgkmcnt(0)
	s_barrier
	ds_read_b128 v[64:67], v96
	ds_read_b128 v[68:71], v96 offset:0x1200
	ds_read_b128 v[72:75], v96 offset:32
	ds_read_b128 v[76:79], v96 offset:0x1220
	ds_read_b128 v[160:163], v96 offset:64
	ds_read_b128 v[164:167], v96 offset:0x1240
	ds_read_b128 v[168:171], v96 offset:96
	ds_read_b128 v[172:175], v96 offset:0x1260
	s_nop 0
	s_waitcnt lgkmcnt(7)
	v_mfma_f32_32x32x16_bf16 v[112:127], v[64:67], v[140:143], v[80:95]
	v_add_u32_e32 v64, s29, v246
	v_add3_u32 v247, v64, v244, s87
	s_waitcnt lgkmcnt(6)
	v_mfma_f32_32x32x16_bf16 v[96:111], v[68:71], v[140:143], v[80:95]
	s_waitcnt lgkmcnt(5)
	v_mfma_f32_32x32x16_bf16 v[112:127], v[72:75], v[136:139], v[112:127]
	s_waitcnt lgkmcnt(4)
	v_mfma_f32_32x32x16_bf16 v[96:111], v[76:79], v[136:139], v[96:111]
	s_waitcnt lgkmcnt(3)
	v_mfma_f32_32x32x16_bf16 v[112:127], v[160:163], v[132:135], v[112:127]
	s_waitcnt lgkmcnt(2)
	v_mfma_f32_32x32x16_bf16 v[96:111], v[164:167], v[132:135], v[96:111]
	s_waitcnt lgkmcnt(1)
	v_mfma_f32_32x32x16_bf16 v[112:127], v[168:171], v[128:131], v[112:127]
	s_waitcnt lgkmcnt(0)
	v_mfma_f32_32x32x16_bf16 v[96:111], v[172:175], v[128:131], v[96:111]
	ds_read_b64 v[188:189], v247
	ds_read_b64 v[190:191], v247 offset:16
	ds_read_b64 v[184:185], v247 offset:32
	ds_read_b64 v[186:187], v247 offset:48
	ds_read_b64 v[180:181], v247 offset:64
	ds_read_b64 v[182:183], v247 offset:80
	ds_read_b64 v[176:177], v247 offset:96
	ds_read_b64 v[178:179], v247 offset:112
	ds_read_b64 v[172:173], v247 offset:0x1100
	ds_read_b64 v[174:175], v247 offset:0x1110
	ds_read_b64 v[168:169], v247 offset:0x1120
	ds_read_b64 v[170:171], v247 offset:0x1130
	ds_read_b64 v[164:165], v247 offset:0x1140
	ds_read_b64 v[166:167], v247 offset:0x1150
	ds_read_b64 v[160:161], v247 offset:0x1160
	ds_read_b64 v[162:163], v247 offset:0x1170
	v_max3_f32 v65, v112, v113, v114
	v_max3_f32 v65, v65, v115, v116
	v_max3_f32 v65, v65, v117, v118
	v_max3_f32 v65, v65, v119, v120
	v_max3_f32 v65, v65, v121, v122
	v_max3_f32 v65, v65, v123, v124
	v_max3_f32 v65, v65, v125, v126
	v_max_f32_e32 v65, v65, v127
	v_max3_f32 v64, v96, v97, v98
	v_max3_f32 v66, v99, v100, v101
	v_max3_f32 v64, v64, v102, v103
	v_max3_f32 v66, v66, v104, v105
	v_max3_f32 v64, v64, v106, v107
	v_max3_f32 v66, v66, v108, v109
	v_max3_f32 v64, v64, v110, v111
	v_max3_f32 v64, v64, v66, v65
	v_mov_b32_e32 v65, v64
	s_nop 1
	v_permlane32_swap_b32_e32 v64, v65
	v_max_f32_e32 v64, v64, v65
	v_cmp_lt_f32_e32 vcc, s80, v64
	s_cbranch_vccz .LBB0_961
	v_max_f32_e32 v80, 0, v64
	v_exp_f32_e64 v64, -v80
	s_nop 0
	v_mov_b32_e32 v81, v64
	v_pk_mul_f32 v[14:15], v[14:15], v[64:65] op_sel_hi:[1,0]
	v_pk_mul_f32 v[12:13], v[12:13], v[64:65] op_sel_hi:[1,0]
	v_pk_mul_f32 v[10:11], v[10:11], v[64:65] op_sel_hi:[1,0]
	v_pk_mul_f32 v[8:9], v[8:9], v[64:65] op_sel_hi:[1,0]
	v_pk_mul_f32 v[6:7], v[6:7], v[64:65] op_sel_hi:[1,0]
	v_pk_mul_f32 v[4:5], v[4:5], v[64:65] op_sel_hi:[1,0]
	v_pk_mul_f32 v[2:3], v[2:3], v[64:65] op_sel_hi:[1,0]
	v_pk_mul_f32 v[0:1], v[0:1], v[64:65] op_sel_hi:[1,0]
	v_pk_mul_f32 v[30:31], v[30:31], v[64:65] op_sel_hi:[1,0]
	v_pk_mul_f32 v[28:29], v[28:29], v[64:65] op_sel_hi:[1,0]
	v_pk_mul_f32 v[26:27], v[26:27], v[64:65] op_sel_hi:[1,0]
	v_pk_mul_f32 v[24:25], v[24:25], v[64:65] op_sel_hi:[1,0]
	v_pk_mul_f32 v[22:23], v[22:23], v[64:65] op_sel_hi:[1,0]
	v_pk_mul_f32 v[20:21], v[20:21], v[64:65] op_sel_hi:[1,0]
	v_pk_mul_f32 v[18:19], v[18:19], v[64:65] op_sel_hi:[1,0]
	v_pk_mul_f32 v[16:17], v[16:17], v[64:65] op_sel_hi:[1,0]
	v_pk_mul_f32 v[62:63], v[62:63], v[64:65] op_sel_hi:[1,0]
	v_pk_mul_f32 v[60:61], v[60:61], v[64:65] op_sel_hi:[1,0]
	v_pk_mul_f32 v[58:59], v[58:59], v[64:65] op_sel_hi:[1,0]
	v_pk_mul_f32 v[56:57], v[56:57], v[64:65] op_sel_hi:[1,0]
	v_pk_mul_f32 v[54:55], v[54:55], v[64:65] op_sel_hi:[1,0]
	v_pk_mul_f32 v[52:53], v[52:53], v[64:65] op_sel_hi:[1,0]
	v_pk_mul_f32 v[50:51], v[50:51], v[64:65] op_sel_hi:[1,0]
	v_pk_mul_f32 v[48:49], v[48:49], v[64:65] op_sel_hi:[1,0]
	v_pk_mul_f32 v[46:47], v[46:47], v[64:65] op_sel_hi:[1,0]
	v_pk_mul_f32 v[44:45], v[44:45], v[64:65] op_sel_hi:[1,0]
	v_pk_mul_f32 v[42:43], v[42:43], v[64:65] op_sel_hi:[1,0]
	v_pk_mul_f32 v[40:41], v[40:41], v[64:65] op_sel_hi:[1,0]
	v_pk_mul_f32 v[38:39], v[38:39], v[64:65] op_sel_hi:[1,0]
	v_pk_mul_f32 v[36:37], v[36:37], v[64:65] op_sel_hi:[1,0]
	v_pk_mul_f32 v[34:35], v[34:35], v[64:65] op_sel_hi:[1,0]
	v_pk_mul_f32 v[32:33], v[32:33], v[64:65] op_sel_hi:[1,0]
	v_pk_add_f32 v[214:215], v[212:213], v[80:81]
	v_pk_mul_f32 v[64:65], v[212:213], v[80:81]
	v_pk_add_f32 v[112:113], v[112:113], v[80:81] op_sel_hi:[1,0] neg_lo:[0,1] neg_hi:[0,1]
	v_mov_b32_e32 v215, v65
	v_pk_add_f32 v[64:65], v[214:215], 0 neg_lo:[1,1] neg_hi:[1,1]
	v_pk_add_f32 v[96:97], v[96:97], v[80:81] op_sel_hi:[1,0] neg_lo:[0,1] neg_hi:[0,1]
	v_pk_add_f32 v[114:115], v[114:115], v[80:81] op_sel_hi:[1,0] neg_lo:[0,1] neg_hi:[0,1]
	v_pk_add_f32 v[98:99], v[98:99], v[80:81] op_sel_hi:[1,0] neg_lo:[0,1] neg_hi:[0,1]
	v_pk_add_f32 v[116:117], v[116:117], v[80:81] op_sel_hi:[1,0] neg_lo:[0,1] neg_hi:[0,1]
	v_pk_add_f32 v[100:101], v[100:101], v[80:81] op_sel_hi:[1,0] neg_lo:[0,1] neg_hi:[0,1]
	v_pk_add_f32 v[118:119], v[118:119], v[80:81] op_sel_hi:[1,0] neg_lo:[0,1] neg_hi:[0,1]
	v_pk_add_f32 v[102:103], v[102:103], v[80:81] op_sel_hi:[1,0] neg_lo:[0,1] neg_hi:[0,1]
	v_pk_add_f32 v[120:121], v[120:121], v[80:81] op_sel_hi:[1,0] neg_lo:[0,1] neg_hi:[0,1]
	v_pk_add_f32 v[104:105], v[104:105], v[80:81] op_sel_hi:[1,0] neg_lo:[0,1] neg_hi:[0,1]
	v_pk_add_f32 v[122:123], v[122:123], v[80:81] op_sel_hi:[1,0] neg_lo:[0,1] neg_hi:[0,1]
	v_pk_add_f32 v[106:107], v[106:107], v[80:81] op_sel_hi:[1,0] neg_lo:[0,1] neg_hi:[0,1]
	v_pk_add_f32 v[124:125], v[124:125], v[80:81] op_sel_hi:[1,0] neg_lo:[0,1] neg_hi:[0,1]
	v_pk_add_f32 v[108:109], v[108:109], v[80:81] op_sel_hi:[1,0] neg_lo:[0,1] neg_hi:[0,1]
	v_mov_b32_e32 v65, v64
	v_mov_b32_e32 v66, v64
	v_mov_b32_e32 v67, v64
	v_mov_b32_e32 v68, v64
	v_mov_b32_e32 v69, v64
	v_mov_b32_e32 v70, v64
	v_mov_b32_e32 v71, v64
	v_mov_b32_e32 v72, v64
	v_mov_b32_e32 v73, v64
	v_mov_b32_e32 v74, v64
	v_mov_b32_e32 v75, v64
	v_mov_b32_e32 v76, v64
	v_mov_b32_e32 v77, v64
	v_mov_b32_e32 v78, v64
	v_mov_b32_e32 v79, v64
	v_pk_add_f32 v[126:127], v[126:127], v[80:81] op_sel_hi:[1,0] neg_lo:[0,1] neg_hi:[0,1]
	v_pk_add_f32 v[110:111], v[110:111], v[80:81] op_sel_hi:[1,0] neg_lo:[0,1] neg_hi:[0,1]
	v_mov_b32_e32 v80, v64
	v_mov_b32_e32 v81, v64
	v_mov_b32_e32 v82, v64
	v_mov_b32_e32 v83, v64
	v_mov_b32_e32 v84, v64
	v_mov_b32_e32 v85, v64
	v_mov_b32_e32 v86, v64
	v_mov_b32_e32 v87, v64
	v_mov_b32_e32 v88, v64
	v_mov_b32_e32 v89, v64
	v_mov_b32_e32 v90, v64
	v_mov_b32_e32 v91, v64
	v_mov_b32_e32 v92, v64
	v_mov_b32_e32 v93, v64
	v_mov_b32_e32 v94, v64
	v_mov_b32_e32 v95, v64
	v_mov_b32_e32 v212, v214
	s_branch .LBB0_962

.LBB0_975:
	s_and_b32 s0, s8, 0x8000
	s_add_i32 s9, s0, 0
	v_add3_u32 v64, s9, v220, v222
	s_waitcnt vmcnt(2)
	ds_write_b128 v64, v[148:151]
	s_and_saveexec_b64 s[0:1], s[2:3]
	v_add3_u32 v64, s9, v221, v223
	ds_write_b128 v64, v[144:147]
	s_or_b64 exec, exec, s[0:1]
	v_add3_u32 v64, s9, v242, v243
	s_waitcnt vmcnt(0)
	v_perm_b32 v65, v156, v152, s85
	v_perm_b32 v66, v156, v152, s86
	v_add_u32_e32 v64, 0x3400, v64
	ds_write2_b32 v64, v65, v66 offset1:34
	v_perm_b32 v65, v157, v153, s85
	v_perm_b32 v66, v157, v153, s86
	ds_write2_b32 v64, v65, v66 offset0:68 offset1:102
	v_perm_b32 v65, v158, v154, s85
	v_perm_b32 v66, v158, v154, s86
	ds_write2_b32 v64, v65, v66 offset0:136 offset1:170
	v_perm_b32 v65, v159, v155, s85
	v_perm_b32 v66, v159, v155, s86
	ds_write2_b32 v64, v65, v66 offset0:204 offset1:238
	v_lshl_add_u64 v[64:65], s[4:5], 0, v[208:209]
	global_load_dwordx4 v[148:151], v[64:65], off
	s_and_saveexec_b64 s[0:1], s[2:3]
	s_cbranch_execz .LBB0_979
	v_lshl_add_u64 v[64:65], s[4:5], 0, v[206:207]
	global_load_dwordx4 v[144:147], v[64:65], off
.LBB0_979:
	s_or_b64 exec, exec, s[0:1]
	v_lshl_add_u64 v[64:65], s[4:5], 0, v[204:205]
	v_add_co_u32_e32 v64, vcc, 0xa808000, v64
	v_add3_u32 v96, s9, v246, v192
	s_nop 0
	v_addc_co_u32_e32 v65, vcc, 0, v65, vcc
	global_load_dwordx4 v[152:155], v[64:65], off
	global_load_dwordx4 v[156:159], v[64:65], off offset:256
	s_waitcnt lgkmcnt(0)
	s_barrier
	ds_read_b128 v[64:67], v96
	ds_read_b128 v[68:71], v96 offset:0x1200
	ds_read_b128 v[72:75], v96 offset:32
	ds_read_b128 v[76:79], v96 offset:0x1220
	ds_read_b128 v[160:163], v96 offset:64
	ds_read_b128 v[164:167], v96 offset:0x1240
	ds_read_b128 v[168:171], v96 offset:96
	ds_read_b128 v[172:175], v96 offset:0x1260
	v_mov_b32_e32 v254, 0xc00
	s_waitcnt lgkmcnt(7)
	v_mfma_f32_32x32x16_bf16 v[112:127], v[64:67], v[140:143], v[80:95]
	v_add_u32_e32 v64, s9, v247
	v_add3_u32 v249, v64, v244, s87
	s_waitcnt lgkmcnt(6)
	v_mfma_f32_32x32x16_bf16 v[96:111], v[68:71], v[140:143], v[80:95]
	s_waitcnt lgkmcnt(5)
	v_mfma_f32_32x32x16_bf16 v[112:127], v[72:75], v[136:139], v[112:127]
	s_waitcnt lgkmcnt(4)
	v_mfma_f32_32x32x16_bf16 v[96:111], v[76:79], v[136:139], v[96:111]
	s_waitcnt lgkmcnt(3)
	v_mfma_f32_32x32x16_bf16 v[112:127], v[160:163], v[132:135], v[112:127]
	s_waitcnt lgkmcnt(2)
	v_mfma_f32_32x32x16_bf16 v[96:111], v[164:167], v[132:135], v[96:111]
	s_waitcnt lgkmcnt(1)
	v_mfma_f32_32x32x16_bf16 v[112:127], v[168:171], v[128:131], v[112:127]
	s_waitcnt lgkmcnt(0)
	v_mfma_f32_32x32x16_bf16 v[96:111], v[172:175], v[128:131], v[96:111]
	ds_read_b64 v[188:189], v249
	ds_read_b64 v[190:191], v249 offset:16
	ds_read_b64 v[184:185], v249 offset:32
	ds_read_b64 v[186:187], v249 offset:48
	ds_read_b64 v[180:181], v249 offset:64
	ds_read_b64 v[182:183], v249 offset:80
	ds_read_b64 v[176:177], v249 offset:96
	ds_read_b64 v[178:179], v249 offset:112
	ds_read_b64 v[172:173], v249 offset:0x1100
	ds_read_b64 v[174:175], v249 offset:0x1110
	ds_read_b64 v[168:169], v249 offset:0x1120
	ds_read_b64 v[170:171], v249 offset:0x1130
	ds_read_b64 v[164:165], v249 offset:0x1140
	ds_read_b64 v[166:167], v249 offset:0x1150
	ds_read_b64 v[160:161], v249 offset:0x1160
	ds_read_b64 v[162:163], v249 offset:0x1170
	v_max3_f32 v65, v112, v113, v114
	v_max3_f32 v65, v65, v115, v116
	v_max3_f32 v65, v65, v117, v118
	v_max3_f32 v65, v65, v119, v120
	v_max3_f32 v65, v65, v121, v122
	v_max3_f32 v65, v65, v123, v124
	v_max3_f32 v65, v65, v125, v126
	v_max_f32_e32 v65, v65, v127
	v_max3_f32 v64, v96, v97, v98
	v_max3_f32 v66, v99, v100, v101
	v_max3_f32 v64, v64, v102, v103
	v_max3_f32 v66, v66, v104, v105
	v_max3_f32 v64, v64, v106, v107
	v_max3_f32 v66, v66, v108, v109
	v_max3_f32 v64, v64, v110, v111
	v_max3_f32 v64, v64, v66, v65
	v_mov_b32_e32 v65, v64
	s_nop 1
	v_permlane32_swap_b32_e32 v64, v65
	v_max_f32_e32 v64, v64, v65
	v_cmp_lt_f32_e32 vcc, s80, v64
	s_cbranch_vccz .LBB0_981
	v_max_f32_e32 v80, 0, v64
	v_exp_f32_e64 v64, -v80
	s_nop 0
	v_mov_b32_e32 v81, v64
	v_pk_mul_f32 v[14:15], v[14:15], v[64:65] op_sel_hi:[1,0]
	v_pk_mul_f32 v[12:13], v[12:13], v[64:65] op_sel_hi:[1,0]
	v_pk_mul_f32 v[10:11], v[10:11], v[64:65] op_sel_hi:[1,0]
	v_pk_mul_f32 v[8:9], v[8:9], v[64:65] op_sel_hi:[1,0]
	v_pk_mul_f32 v[6:7], v[6:7], v[64:65] op_sel_hi:[1,0]
	v_pk_mul_f32 v[4:5], v[4:5], v[64:65] op_sel_hi:[1,0]
	v_pk_mul_f32 v[2:3], v[2:3], v[64:65] op_sel_hi:[1,0]
	v_pk_mul_f32 v[0:1], v[0:1], v[64:65] op_sel_hi:[1,0]
	v_pk_mul_f32 v[62:63], v[62:63], v[64:65] op_sel_hi:[1,0]
	v_pk_mul_f32 v[60:61], v[60:61], v[64:65] op_sel_hi:[1,0]
	v_pk_mul_f32 v[58:59], v[58:59], v[64:65] op_sel_hi:[1,0]
	v_pk_mul_f32 v[56:57], v[56:57], v[64:65] op_sel_hi:[1,0]
	v_pk_mul_f32 v[54:55], v[54:55], v[64:65] op_sel_hi:[1,0]
	v_pk_mul_f32 v[52:53], v[52:53], v[64:65] op_sel_hi:[1,0]
	v_pk_mul_f32 v[50:51], v[50:51], v[64:65] op_sel_hi:[1,0]
	v_pk_mul_f32 v[48:49], v[48:49], v[64:65] op_sel_hi:[1,0]
	v_pk_mul_f32 v[46:47], v[46:47], v[64:65] op_sel_hi:[1,0]
	v_pk_mul_f32 v[44:45], v[44:45], v[64:65] op_sel_hi:[1,0]
	v_pk_mul_f32 v[42:43], v[42:43], v[64:65] op_sel_hi:[1,0]
	v_pk_mul_f32 v[40:41], v[40:41], v[64:65] op_sel_hi:[1,0]
	v_pk_mul_f32 v[38:39], v[38:39], v[64:65] op_sel_hi:[1,0]
	v_pk_mul_f32 v[36:37], v[36:37], v[64:65] op_sel_hi:[1,0]
	v_pk_mul_f32 v[34:35], v[34:35], v[64:65] op_sel_hi:[1,0]
	v_pk_mul_f32 v[32:33], v[32:33], v[64:65] op_sel_hi:[1,0]
	v_pk_mul_f32 v[30:31], v[30:31], v[64:65] op_sel_hi:[1,0]
	v_pk_mul_f32 v[28:29], v[28:29], v[64:65] op_sel_hi:[1,0]
	v_pk_mul_f32 v[26:27], v[26:27], v[64:65] op_sel_hi:[1,0]
	v_pk_mul_f32 v[24:25], v[24:25], v[64:65] op_sel_hi:[1,0]
	v_pk_mul_f32 v[22:23], v[22:23], v[64:65] op_sel_hi:[1,0]
	v_pk_mul_f32 v[20:21], v[20:21], v[64:65] op_sel_hi:[1,0]
	v_pk_mul_f32 v[18:19], v[18:19], v[64:65] op_sel_hi:[1,0]
	v_pk_mul_f32 v[16:17], v[16:17], v[64:65] op_sel_hi:[1,0]
	v_pk_add_f32 v[212:213], v[210:211], v[80:81]
	v_pk_mul_f32 v[64:65], v[210:211], v[80:81]
	v_pk_add_f32 v[112:113], v[112:113], v[80:81] op_sel_hi:[1,0] neg_lo:[0,1] neg_hi:[0,1]
	v_mov_b32_e32 v213, v65
	v_pk_add_f32 v[64:65], v[212:213], 0 neg_lo:[1,1] neg_hi:[1,1]
	v_pk_add_f32 v[96:97], v[96:97], v[80:81] op_sel_hi:[1,0] neg_lo:[0,1] neg_hi:[0,1]
	v_pk_add_f32 v[114:115], v[114:115], v[80:81] op_sel_hi:[1,0] neg_lo:[0,1] neg_hi:[0,1]
	v_pk_add_f32 v[98:99], v[98:99], v[80:81] op_sel_hi:[1,0] neg_lo:[0,1] neg_hi:[0,1]
	v_pk_add_f32 v[116:117], v[116:117], v[80:81] op_sel_hi:[1,0] neg_lo:[0,1] neg_hi:[0,1]
	v_pk_add_f32 v[100:101], v[100:101], v[80:81] op_sel_hi:[1,0] neg_lo:[0,1] neg_hi:[0,1]
	v_pk_add_f32 v[118:119], v[118:119], v[80:81] op_sel_hi:[1,0] neg_lo:[0,1] neg_hi:[0,1]
	v_pk_add_f32 v[102:103], v[102:103], v[80:81] op_sel_hi:[1,0] neg_lo:[0,1] neg_hi:[0,1]
	v_pk_add_f32 v[120:121], v[120:121], v[80:81] op_sel_hi:[1,0] neg_lo:[0,1] neg_hi:[0,1]
	v_pk_add_f32 v[104:105], v[104:105], v[80:81] op_sel_hi:[1,0] neg_lo:[0,1] neg_hi:[0,1]
	v_pk_add_f32 v[122:123], v[122:123], v[80:81] op_sel_hi:[1,0] neg_lo:[0,1] neg_hi:[0,1]
	v_pk_add_f32 v[106:107], v[106:107], v[80:81] op_sel_hi:[1,0] neg_lo:[0,1] neg_hi:[0,1]
	v_pk_add_f32 v[124:125], v[124:125], v[80:81] op_sel_hi:[1,0] neg_lo:[0,1] neg_hi:[0,1]
	v_pk_add_f32 v[108:109], v[108:109], v[80:81] op_sel_hi:[1,0] neg_lo:[0,1] neg_hi:[0,1]
	v_mov_b32_e32 v65, v64
	v_mov_b32_e32 v66, v64
	v_mov_b32_e32 v67, v64
	v_mov_b32_e32 v68, v64
	v_mov_b32_e32 v69, v64
	v_mov_b32_e32 v70, v64
	v_mov_b32_e32 v71, v64
	v_mov_b32_e32 v72, v64
	v_mov_b32_e32 v73, v64
	v_mov_b32_e32 v74, v64
	v_mov_b32_e32 v75, v64
	v_mov_b32_e32 v76, v64
	v_mov_b32_e32 v77, v64
	v_mov_b32_e32 v78, v64
	v_mov_b32_e32 v79, v64
	v_pk_add_f32 v[126:127], v[126:127], v[80:81] op_sel_hi:[1,0] neg_lo:[0,1] neg_hi:[0,1]
	v_pk_add_f32 v[110:111], v[110:111], v[80:81] op_sel_hi:[1,0] neg_lo:[0,1] neg_hi:[0,1]
	v_mov_b32_e32 v80, v64
	v_mov_b32_e32 v81, v64
	v_mov_b32_e32 v82, v64
	v_mov_b32_e32 v83, v64
	v_mov_b32_e32 v84, v64
	v_mov_b32_e32 v85, v64
	v_mov_b32_e32 v86, v64
	v_mov_b32_e32 v87, v64
	v_mov_b32_e32 v88, v64
	v_mov_b32_e32 v89, v64
	v_mov_b32_e32 v90, v64
	v_mov_b32_e32 v91, v64
	v_mov_b32_e32 v92, v64
	v_mov_b32_e32 v93, v64
	v_mov_b32_e32 v94, v64
	v_mov_b32_e32 v95, v64
	v_mov_b32_e32 v210, v212
	s_branch .LBB0_982
